# P8 sample w_out GEMM also split in K over 32 workgroups (partials through dead qkv workspace, flag generation 1; P12 flags generation 2)
# baseline (speedup 1.0000x reference)
; #define PH(k) if (a.ph_lo <= (k) && (k) < a.ph_hi) { if ((k) > a.ph_lo && (k) != 6) SEAM(k);
; #define GEMM_N1024(EPI, Aoff, Woff, Mrows, Kdim, rowbase, Gn, cid, ...) do { pg8::Gemm g{(const bf16_t*)(a.ws + (Aoff)) + (size_t)(rowbase) * (Kdim), (const bf16_t*)(a.ws + (Woff)), (Mrows), 1024, (Kdim)}; \
;         pg8::StaticOrder S; S.init((Mrows), 1024, (Gn), (cid)); EPI E{__VA_ARGS__, (rowbase)}; pg8::gemm_phase<EPI, pg8::StaticOrder, false, true>(lds, g, S, E); } while (0)
; __device__ __forceinline__ void row_pass1(const Args& a, int row_lo, int row_hi, int gw, int NGW, int lane) {
;     const bf16_t* Y = (const bf16_t*)(a.ws + A_GB); bf16_t* A2 = (bf16_t*)(a.ws + A_RB); const float* rss = (const float*)(a.ws + WS_RSS1); float* XO = a.out + O_Y;
;     f32x4 gp[4], gq[4];
; #pragma unroll
;     for (int j = 0; j < 4; ++j) { gp[j] = ((const f32x4*)a.in[I_NMPOST])[lane + 64 * j]; gq[j] = ((const f32x4*)a.in[I_NFPRE])[lane + 64 * j]; }
;     for (int r0 = row_lo + 2 * gw; r0 < row_hi; r0 += 2 * NGW) {
; __global__ void __launch_bounds__(512) fwd_kernel(Args a) {
;     ...
;     PH(8) {
;         if (G >= 32 && bx < 16) GEMM_N1024(EpiN1024<2>, A_GA, WS_WOUT, MS, 1024, MP, 16, bx, (bf16_t*)(a.ws + A_GB), nullptr, (float*)(a.ws + WS_RSS1));
;         else if (G >= 32) row_pass1(a, 0, MP, gw - 128, NGW - 128, lane);
;         else { row_pass1(a, 0, MP, gw, NGW, lane); GEMM_N1024(EpiN1024<2>, A_GA, WS_WOUT, MS, 1024, MP, G, bx, (bf16_t*)(a.ws + A_GB), nullptr, (float*)(a.ws + WS_RSS1)); }
.LBB0_989:
	s_cmp_lt_i32 s58, 32
	s_cselect_b64 s[0:1], -1, 0
	s_cmp_gt_i32 s58, 31
	s_cselect_b64 s[6:7], -1, 0
	s_cmp_lt_i32 s2, 32
	s_cselect_b64 s[8:9], -1, 0
	s_and_b64 s[6:7], s[8:9], s[6:7]
	s_andn2_b64 vcc, exec, s[6:7]
	s_mov_b64 s[6:7], -1
	s_cbranch_vccz .LBB0_1043
	v_readlane_b32 s16, v252, 1
	v_lshlrev_b32_e32 v160, 4, v176
	v_readlane_b32 s28, v252, 13
	v_readlane_b32 s29, v252, 14
	v_readlane_b32 s30, v252, 15
	v_readlane_b32 s31, v252, 16
	s_nop 2
	global_load_dwordx4 v[0:3], v160, s[28:29]
	s_waitcnt lgkmcnt(0)
	global_load_dwordx4 v[4:7], v160, s[30:31]
	global_load_dwordx4 v[8:11], v160, s[28:29] offset:1024
	global_load_dwordx4 v[12:15], v160, s[30:31] offset:1024
	global_load_dwordx4 v[16:19], v160, s[28:29] offset:2048
	global_load_dwordx4 v[20:23], v160, s[30:31] offset:2048
	global_load_dwordx4 v[24:27], v160, s[28:29] offset:3072
	global_load_dwordx4 v[28:31], v160, s[30:31] offset:3072
	s_add_u32 s6, s54, 0x2280000
	s_addc_u32 s7, s55, 0
	s_mov_b64 s[10:11], -1
	s_and_b64 vcc, exec, s[0:1]
	v_readlane_b32 s17, v252, 2
	v_readlane_b32 s18, v252, 3
	v_readlane_b32 s19, v252, 4
	v_readlane_b32 s20, v252, 5
	v_readlane_b32 s21, v252, 6
	v_readlane_b32 s22, v252, 7
	v_readlane_b32 s23, v252, 8
	v_readlane_b32 s24, v252, 9
	v_readlane_b32 s25, v252, 10
	v_readlane_b32 s26, v252, 11
	v_readlane_b32 s27, v252, 12
	s_cbranch_vccz .LBB0_1036
	s_cmpk_gt_i32 s81, 0x1fff
	s_cbranch_scc1 .LBB0_996
	v_mov_b32_e32 v161, 0
	v_lshlrev_b32_e32 v32, 3, v176
	v_mov_b32_e32 v33, v161
	v_lshl_add_u64 v[34:35], s[54:55], 0, v[32:33]
	v_mbcnt_lo_u32_b32 v33, -1, 0
	s_mov_b64 s[0:1], 0xde00000
	v_mbcnt_hi_u32_b32 v33, -1, v33
	s_waitcnt vmcnt(0)
	v_lshl_add_u64 v[48:49], v[34:35], 0, s[0:1]
	v_and_b32_e32 v34, 64, v33
	v_add_u32_e32 v34, 64, v34
	v_xor_b32_e32 v35, 32, v33
	v_cmp_lt_i32_e32 vcc, v35, v34
	s_lshl_b32 s10, s81, 1
	s_ashr_i32 s11, s10, 31
	v_cndmask_b32_e32 v35, v33, v35, vcc
	v_lshlrev_b32_e32 v64, 2, v35
	v_xor_b32_e32 v35, 16, v33
	v_cmp_lt_i32_e32 vcc, v35, v34
	s_lshl_b32 s14, s58, 4
	s_lshl_b64 s[0:1], s[10:11], 12
	v_cndmask_b32_e32 v35, v33, v35, vcc
	v_lshlrev_b32_e32 v65, 2, v35
	v_xor_b32_e32 v35, 8, v33
	v_cmp_lt_i32_e32 vcc, v35, v34
	s_add_u32 s16, s52, s0
	s_addc_u32 s17, s53, s1
	v_cndmask_b32_e32 v35, v33, v35, vcc
	v_lshlrev_b32_e32 v66, 2, v35
	v_xor_b32_e32 v35, 4, v33
	v_cmp_lt_i32_e32 vcc, v35, v34
	s_ashr_i32 s15, s14, 31
	s_lshl_b64 s[20:21], s[10:11], 11
	v_cndmask_b32_e32 v35, v33, v35, vcc
	v_lshlrev_b32_e32 v67, 2, v35
	v_xor_b32_e32 v35, 2, v33
	v_cmp_lt_i32_e32 vcc, v35, v34
	s_lshl_b64 s[18:19], s[14:15], 12
	v_or_b32_e32 v50, s20, v32
	v_cndmask_b32_e32 v35, v33, v35, vcc
	v_mov_b32_e32 v51, s21
	s_lshl_b64 s[20:21], s[14:15], 11
	s_lshl_b64 s[22:23], s[10:11], 2
	v_lshlrev_b32_e32 v68, 2, v35
	v_xor_b32_e32 v35, 1, v33
	s_add_u32 s11, s22, 0x2280000
	v_cmp_lt_i32_e32 vcc, v35, v34
	s_addc_u32 s26, s23, 0
	s_lshl_b64 s[22:23], s[14:15], 2
	v_readlane_b32 s36, v252, 1
	v_cndmask_b32_e32 v33, v33, v35, vcc
	v_readlane_b32 s37, v252, 2
	s_add_u32 s24, s36, s0
	v_lshlrev_b32_e32 v69, 2, v33
	s_addc_u32 s25, s37, s1
	s_mov_b32 s15, 0xde00000
	v_mov_b32_e32 v70, 0x358637bd
	s_mov_b32 s27, 0x800000
	s_mov_b32 s28, 0x9a00000
	s_movk_i32 s29, 0x1000
	v_readlane_b32 s38, v252, 3
	v_readlane_b32 s39, v252, 4
	v_readlane_b32 s40, v252, 5
	v_readlane_b32 s41, v252, 6
	v_readlane_b32 s42, v252, 7
	v_readlane_b32 s43, v252, 8
	v_readlane_b32 s44, v252, 9
	v_readlane_b32 s45, v252, 10
	v_readlane_b32 s46, v252, 11
	v_readlane_b32 s47, v252, 12
	v_readlane_b32 s48, v252, 13
	v_readlane_b32 s49, v252, 14
	v_readlane_b32 s50, v252, 15
	v_readlane_b32 s51, v252, 16
	s_branch .LBB0_994

; __device__ __forceinline__ void row_pass1(const Args& a, int row_lo, int row_hi, int gw, int NGW, int lane) {
;     const bf16_t* Y = (const bf16_t*)(a.ws + A_GB); bf16_t* A2 = (bf16_t*)(a.ws + A_RB); const float* rss = (const float*)(a.ws + WS_RSS1); float* XO = a.out + O_Y;
;     f32x4 gp[4], gq[4];
; #pragma unroll
;     for (int j = 0; j < 4; ++j) { gp[j] = ((const f32x4*)a.in[I_NMPOST])[lane + 64 * j]; gq[j] = ((const f32x4*)a.in[I_NFPRE])[lane + 64 * j]; }
;     for (int r0 = row_lo + 2 * gw; r0 < row_hi; r0 += 2 * NGW) {
;         f32x4 xv[2][4]; u32x2 yv[2][4]; float rs[2];
; #pragma unroll
;         for (int r = 0; r < 2; ++r) { const int row = (r0 + r < row_hi) ? r0 + r : r0; rs[r] = rss[row];
;             const f32x4* xr = (const f32x4*)xrow_ptr(a, row) + lane; const u32x2* yr = (const u32x2*)(Y + (size_t)row * DM) + lane;
; __global__ void __launch_bounds__(512) fwd_kernel(Args a) {
;     ...
;         else if (G >= 32) row_pass1(a, 0, MP, gw - 128, NGW - 128, lane);
.LBB0_1036:
	s_and_b64 vcc, exec, s[10:11]
	s_cbranch_vccz .LBB0_1042
	s_lshl_b32 s0, s81, 1
	s_add_i32 s8, s0, 0xfffffe00
	s_cmpk_gt_i32 s8, 0x3fff
	s_cbranch_scc1 .LBB0_1042
	v_mov_b32_e32 v161, 0
	v_lshlrev_b32_e32 v32, 3, v176
	v_mov_b32_e32 v33, v161
	v_lshl_add_u64 v[34:35], s[54:55], 0, v[32:33]
	v_mbcnt_lo_u32_b32 v33, -1, 0
	s_mov_b64 s[0:1], 0xde00000
	v_mbcnt_hi_u32_b32 v33, -1, v33
	s_waitcnt vmcnt(0)
	v_lshl_add_u64 v[48:49], v[34:35], 0, s[0:1]
	v_and_b32_e32 v34, 64, v33
	v_add_u32_e32 v34, 64, v34
	v_xor_b32_e32 v35, 32, v33
	v_cmp_lt_i32_e32 vcc, v35, v34
	s_lshl_b32 s0, s58, 4
	s_ashr_i32 s9, s8, 31
	v_cndmask_b32_e32 v35, v33, v35, vcc
	v_lshlrev_b32_e32 v64, 2, v35
	v_xor_b32_e32 v35, 16, v33
	v_cmp_lt_i32_e32 vcc, v35, v34
	s_add_i32 s10, s0, 0xfffffe00
	s_lshl_b64 s[0:1], s[8:9], 12
	v_cndmask_b32_e32 v35, v33, v35, vcc
	v_lshlrev_b32_e32 v65, 2, v35
	v_xor_b32_e32 v35, 8, v33
	v_cmp_lt_i32_e32 vcc, v35, v34
	s_add_u32 s14, s52, s0
	s_addc_u32 s15, s53, s1
	v_cndmask_b32_e32 v35, v33, v35, vcc
	v_lshlrev_b32_e32 v66, 2, v35
	v_xor_b32_e32 v35, 4, v33
	v_cmp_lt_i32_e32 vcc, v35, v34
	s_ashr_i32 s11, s10, 31
	s_lshl_b64 s[18:19], s[8:9], 11
	v_cndmask_b32_e32 v35, v33, v35, vcc
	v_lshlrev_b32_e32 v67, 2, v35
	v_xor_b32_e32 v35, 2, v33
	v_cmp_lt_i32_e32 vcc, v35, v34
	s_lshl_b64 s[16:17], s[10:11], 12
	v_or_b32_e32 v50, s18, v32
	v_cndmask_b32_e32 v35, v33, v35, vcc
	v_mov_b32_e32 v51, s19
	s_lshl_b64 s[18:19], s[10:11], 11
	s_lshl_b64 s[20:21], s[8:9], 2
	v_lshlrev_b32_e32 v68, 2, v35
	v_xor_b32_e32 v35, 1, v33
	s_add_u32 s9, s20, 0x2280000
	v_cmp_lt_i32_e32 vcc, v35, v34
	s_addc_u32 s24, s21, 0
	s_lshl_b64 s[20:21], s[10:11], 2
	v_readlane_b32 s36, v252, 1
	v_cndmask_b32_e32 v33, v33, v35, vcc
	v_readlane_b32 s37, v252, 2
	s_add_u32 s22, s36, s0
	v_lshlrev_b32_e32 v69, 2, v33
	s_addc_u32 s23, s37, s1
	s_mov_b32 s11, 0xde00000
	v_mov_b32_e32 v70, 0x358637bd
	s_mov_b32 s25, 0x800000
	s_mov_b32 s26, 0x9a00000
	s_movk_i32 s27, 0x1000
	v_readlane_b32 s38, v252, 3
	v_readlane_b32 s39, v252, 4
	v_readlane_b32 s40, v252, 5
	v_readlane_b32 s41, v252, 6
	v_readlane_b32 s42, v252, 7
	v_readlane_b32 s43, v252, 8
	v_readlane_b32 s44, v252, 9
	v_readlane_b32 s45, v252, 10
	v_readlane_b32 s46, v252, 11
	v_readlane_b32 s47, v252, 12
	v_readlane_b32 s48, v252, 13
	v_readlane_b32 s49, v252, 14
	v_readlane_b32 s50, v252, 15
	v_readlane_b32 s51, v252, 16
	s_branch .LBB0_1040

;     __host__ __device__ bool next(int i, Unit& u) const {
;         const long L = (long)i * G + c; if (L >= nwg) return false;
;         int wgid = (int)L; { const int q = nwg / NXCD, r = nwg % NXCD, xcd = wgid % NXCD, off = wgid / NXCD; wgid = (xcd < r ? xcd * (q + 1) : r * (q + 1) + (xcd - r) * q) + off; }
;         const int nig = WGM * nN, gid = wgid / nig, fm = gid * WGM, gsz = (nM - fm) < WGM ? (nM - fm) : WGM;
;         u.pm = fm + ((wgid % nig) % gsz); u.pn = (wgid % nig) / gsz; return true;
.LBB0_1043:
	s_andn2_b64 vcc, exec, s[6:7]
	s_cbranch_vccnz .LBB0_1079
	s_and_b32 s98, s2, 15
	s_ashr_i32 s40, s2, 31
	s_lshr_b32 s0, s40, 29
	s_add_i32 s6, s98, s0
	s_and_b32 s0, s6, -8
	s_sub_i32 s3, s98, s0
	s_cmp_gt_i32 s3, -1
	v_readfirstlane_b32 s41, v178
	s_cbranch_scc0 .LBB0_1046
	s_lshl_b32 s7, s3, 1
	s_cbranch_execz .LBB0_1047
	s_branch .LBB0_1048

; #define PG8_STAGE(bufoff, gbase, voff) do { _Pragma("unroll") for (int _i = 0; _i < 2; ++_i) \
;         __builtin_amdgcn_global_load_lds((const unsigned*)((const char*)(gbase) + (voff)[_i]), (PG8_LAS unsigned*)(lds + (bufoff) + ldsw + _i * 8192), 16, 0, 0); } while (0)
; #define PG8_WAIT_V(n) asm volatile("s_waitcnt vmcnt(" #n ")" ::: "memory")
; #define PG8_BAR __builtin_amdgcn_s_barrier()
; template <class Epi, class Sched, bool ALIGN_EPI = false, bool SP2 = false>
; __device__ __forceinline__ void gemm_phase(PG8_LAS unsigned char* lds, const Gemm g, const Sched& S, const Epi& E) {
;     ...
;     for (int i = 0; i < 2; ++i) { int R, C; stage_rc(tid * 16 + i * 8192, R, C); const int Rb = Epi::PERM ? ((R & ~31) + perm32(R & 31)) : R;
;         voffA[i] = (unsigned)(R * K + C) * 2u; voffB[i] = (unsigned)(Rb * K + C) * 2u; }
;     ...
;     const char* cA = (const char*)g.A + (size_t)cur.pm * tstep; const char* cB = (const char*)g.Bt + (size_t)cur.pn * tstep;
;     S.a_ready(cur);
;     if constexpr (SP2) {
;         PG8_STAGE(PG8_SB(0, 0), cB, voffB); PG8_STAGE(PG8_SB(0, 1), cB + hstep, voffB); PG8_STAGE(PG8_SA(0, 0), cA, voffA); PG8_STAGE(PG8_SA(0, 1), cA + hstep, voffA);
;         if (wr == 1) PG8_BAR;
;         PG8_WAIT_V(2); PG8_BAR;
;         PG8_STAGE(PG8_SB(1, 0), cB + kstep, voffB); PG8_STAGE(PG8_SA(1, 0), cA + kstep, voffA); PG8_STAGE(PG8_SB(1, 1), cB + hstep + kstep, voffB);
;         PG8_WAIT_V(6); PG8_BAR;
.LBB0_1048:
	s_add_u32 s42, s54, 0xdc00000
	s_waitcnt vmcnt(0)
	v_lshlrev_b32_e32 v0, 4, v178
	s_addc_u32 s43, s55, 0
	v_and_b32_e32 v1, 32, v178
	v_bfe_u32 v10, v178, 2, 4
	v_lshrrev_b32_e32 v2, 3, v178
	s_movk_i32 s0, 0x70
	v_add_u32_e32 v11, 0x2000, v0
	s_add_u32 s44, s54, 0x1000000
	v_bitop3_b32 v8, v0, v1, 48 bitop3:0x6c
	v_and_or_b32 v2, v2, s0, v10
	v_lshrrev_b32_e32 v0, 7, v11
	s_movk_i32 s0, 0xf0
	s_addc_u32 s45, s55, 0
	s_lshr_b32 s99, s2, 4
	s_lshl_b32 s99, s99, 10
	s_add_u32 s42, s42, s99
	s_addc_u32 s43, s43, 0
	s_add_u32 s44, s44, s99
	s_addc_u32 s45, s45, 0
	v_and_or_b32 v0, v0, s0, v10
	s_ashr_i32 s0, s6, 3
	s_add_i32 s0, s7, s0
	s_ashr_i32 s6, s0, 31
	s_lshr_b32 s6, s6, 27
	s_add_i32 s6, s0, s6
	s_ashr_i32 s6, s6, 5
	s_lshl_b32 s8, s6, 3
	v_and_b32_e32 v9, 64, v178
	s_sub_i32 s7, 4, s8
	s_lshl_b32 s6, s6, 5
	v_or_b32_e32 v1, v8, v9
	s_min_u32 s9, s7, 8
	s_sub_i32 s10, s0, s6
	v_lshl_or_b32 v128, v2, 11, v1
	v_lshl_or_b32 v130, v0, 11, v1
	s_sext_i32_i8 s0, s10
	v_cvt_f32_ubyte0_e32 v1, s9
	v_cvt_f32_i32_e32 v0, s0
	v_rcp_iflag_f32_e32 v2, v1
	s_lshr_b32 s3, s41, 6
	s_ashr_i32 s0, s0, 30
	s_lshr_b32 s1, s41, 8
	v_mul_f32_e32 v2, v0, v2
	v_trunc_f32_e32 v2, v2
	v_fma_f32 v0, -v2, v1, v0
	v_cvt_i32_f32_e32 v2, v2
	s_lshl_b32 s46, s3, 10
	s_or_b32 s0, s0, 1
	v_cmp_ge_f32_e64 s[6:7], |v0|, v1
	s_and_b64 s[6:7], s[6:7], exec
	s_cselect_b32 s0, s0, 0
	v_readfirstlane_b32 s6, v2
	s_add_i32 s0, s6, s0
	s_mul_i32 s6, s0, s9
	s_sub_i32 s6, s10, s6
	s_sext_i32_i8 s6, s6
	s_add_i32 s26, s8, s6
	s_ashr_i32 s27, s26, 31
	s_bfe_i64 s[8:9], s[0:1], 0x80000
	s_lshl_b64 s[6:7], s[26:27], 19
	s_lshl_b64 s[8:9], s[8:9], 19
	s_add_u32 s30, s44, s8
	s_addc_u32 s31, s45, s9
	s_add_i32 s47, s46, 0
	s_add_i32 m0, s47, 0x10000
	v_mov_b32_e32 v129, 0
	global_load_lds_dwordx4 v128, s[30:31]
	s_add_i32 m0, s47, 0x12000
	s_add_u32 s8, s30, 0x40000
	global_load_lds_dwordx4 v130, s[30:31]
	s_addc_u32 s9, s31, 0
	s_add_i32 m0, s47, 0x14000
	v_mov_b32_e32 v131, v129
	global_load_lds_dwordx4 v128, s[8:9]
	s_add_i32 m0, s47, 0x16000
	s_add_u32 s28, s42, s6
	s_addc_u32 s29, s43, s7
	s_add_i32 s60, s47, 0x2000
	global_load_lds_dwordx4 v130, s[8:9]
	s_mov_b32 m0, s47
	s_add_u32 s6, s28, 0x40000
	global_load_lds_dwordx4 v128, s[28:29]
	s_mov_b32 m0, s60
	s_addc_u32 s7, s29, 0
	s_add_i32 s61, s47, 0x4000
	global_load_lds_dwordx4 v130, s[28:29]
	s_mov_b32 m0, s61
	s_add_i32 s62, s47, 0x6000
	global_load_lds_dwordx4 v128, s[6:7]
	s_mov_b32 m0, s62
	v_lshl_add_u64 v[6:7], s[30:31], 0, v[128:129]
	global_load_lds_dwordx4 v130, s[6:7]
	s_mov_b32 s7, 0
	s_waitcnt lgkmcnt(0)
	v_lshl_add_u64 v[4:5], s[30:31], 0, v[130:131]
	v_lshl_add_u64 v[2:3], s[28:29], 0, v[128:129]
	s_cmp_lg_u32 s1, 1
	v_lshl_add_u64 v[0:1], s[28:29], 0, v[130:131]
	s_cbranch_scc1 .LBB0_1050
	s_barrier

; #define PG8_STAGE(bufoff, gbase, voff) do { _Pragma("unroll") for (int _i = 0; _i < 2; ++_i) \
;         __builtin_amdgcn_global_load_lds((const unsigned*)((const char*)(gbase) + (voff)[_i]), (PG8_LAS unsigned*)(lds + (bufoff) + ldsw + _i * 8192), 16, 0, 0); } while (0)
; #define PG8_LDA(dst, b, h) do { _Pragma("unroll") for (int m = 0; m < 4; ++m) _Pragma("unroll") for (int k = 0; k < 2; ++k) dst[m][k] = *(const PG8_LAS bf16x8*)(lds + PG8_SA(b, h) + aoff + m * 2048 + k * 1024); } while (0)
; #define PG8_LDB(dst, b, h) do { _Pragma("unroll") for (int n = 0; n < 2; ++n) _Pragma("unroll") for (int k = 0; k < 2; ++k) dst[n][k] = *(const PG8_LAS bf16x8*)(lds + PG8_SB(b, h) + boff + n * 2048 + k * 1024); } while (0)
; #define PG8_MMA(ai, bj, At, Bt) do { __builtin_amdgcn_s_setprio(1); _Pragma("unroll") for (int m = 0; m < 4; ++m) _Pragma("unroll") for (int n = 0; n < 2; ++n) _Pragma("unroll") for (int k = 0; k < 2; ++k) \
;         acc[ai][bj][m][n] = __builtin_amdgcn_mfma_f32_16x16x32_bf16(Bt[n][k], At[m][k], acc[ai][bj][m][n], 0, 0, 0); __builtin_amdgcn_s_setprio(0); } while (0)
; #define PG8_WAIT_V(n) asm volatile("s_waitcnt vmcnt(" #n ")" ::: "memory")
; #define PG8_BAR __builtin_amdgcn_s_barrier()
; template <class Epi, class Sched, bool ALIGN_EPI = false, bool SP2 = false>
; __device__ __forceinline__ void gemm_phase(PG8_LAS unsigned char* lds, const Gemm g, const Sched& S, const Epi& E) {
;     ...
;         for (int t = 0; t < nt; t += 2) {
;             const bool last = (t == nt - 2);
;             const char* a1 = cA + (size_t)(t + 1) * kstep;
;             const char* a2 = last ? nA : cA + (size_t)(t + 2) * kstep; const char* b2 = last ? nB : cB + (size_t)(t + 2) * kstep;
;             const char* a3 = a2 + kstep; const char* b3 = b2 + kstep;
;             if (last && has_next) S.a_ready(nxt);
;             if constexpr (SP2) {
;             PG8_LDB(B0, 0, 0); PG8_LDB(B1, 0, 1); PG8_SCHED; PG8_LDA(At, 0, 0); PG8_STAGE(PG8_SA(1, 1), a1 + hstep, voffA);
;             PG8_WAIT_V(8); PG8_WAIT_L(0); PG8_BAR; PG8_MMA(0, 0, At, B0); PG8_MMA(0, 1, At, B1); PG8_BAR; PG8_SCHED;
;             PG8_LDA(At, 0, 1); PG8_STAGE(PG8_SB(0, 0), b2, voffB); PG8_STAGE(PG8_SB(0, 1), b2 + hstep, voffB); PG8_STAGE(PG8_SA(0, 0), a2, voffA);
;             PG8_WAIT_V(8); PG8_WAIT_L(0); PG8_BAR; PG8_MMA(1, 0, At, B0); PG8_MMA(1, 1, At, B1); PG8_BAR; PG8_SCHED;
.LBB0_1059:
	ds_read_b128 v[136:139], v143
	ds_read_b128 v[148:151], v143 offset:1024
	ds_read_b128 v[152:155], v143 offset:2048
	ds_read_b128 v[156:159], v143 offset:3072
	ds_read_b128 v[160:163], v144
	ds_read_b128 v[164:167], v144 offset:1024
	ds_read_b128 v[168:171], v144 offset:2048
	ds_read_b128 v[172:175], v144 offset:3072
	s_add_u32 s3, s28, 0xfffc0080
	s_addc_u32 s30, s29, -1
	s_cmp_eq_u32 s71, 4
	s_cselect_b32 s35, s21, s30
	s_cselect_b32 s34, s67, s3
	s_cselect_b32 s31, s19, s70
	s_cselect_b32 s30, s68, s69
	v_lshl_add_u64 v[212:213], s[28:29], 0, v[132:133]
	s_add_i32 m0, s47, 0xc000
	ds_read_b128 v[180:183], v145
	ds_read_b128 v[184:187], v145 offset:1024
	ds_read_b128 v[188:191], v145 offset:2048
	ds_read_b128 v[192:195], v145 offset:3072
	ds_read_b128 v[196:199], v145 offset:4096
	ds_read_b128 v[200:203], v145 offset:5120
	ds_read_b128 v[204:207], v145 offset:6144
	ds_read_b128 v[208:211], v145 offset:7168
	global_load_lds_dwordx4 v[212:213], off
	v_lshl_add_u64 v[212:213], s[28:29], 0, v[134:135]
	s_add_i32 m0, s47, 0xe000
	s_nop 0
	global_load_lds_dwordx4 v[212:213], off
	s_waitcnt vmcnt(8)
	s_waitcnt lgkmcnt(0)
	s_barrier
	s_setprio 1
	s_waitcnt lgkmcnt(0)
	v_mfma_f32_16x16x32_bf16 v[124:127], v[136:139], v[180:183], v[124:127]
	v_mfma_f32_16x16x32_bf16 v[120:123], v[152:155], v[180:183], v[120:123]
	v_mfma_f32_16x16x32_bf16 v[112:115], v[136:139], v[188:191], v[112:115]
	v_mfma_f32_16x16x32_bf16 v[104:107], v[152:155], v[188:191], v[104:107]
	v_mfma_f32_16x16x32_bf16 v[96:99], v[136:139], v[196:199], v[96:99]
	v_mfma_f32_16x16x32_bf16 v[88:91], v[152:155], v[196:199], v[88:91]
	v_mfma_f32_16x16x32_bf16 v[80:83], v[136:139], v[204:207], v[80:83]
	v_mfma_f32_16x16x32_bf16 v[72:75], v[152:155], v[204:207], v[72:75]
	v_mfma_f32_16x16x32_bf16 v[124:127], v[148:151], v[184:187], v[124:127]
	v_mfma_f32_16x16x32_bf16 v[120:123], v[156:159], v[184:187], v[120:123]
	v_mfma_f32_16x16x32_bf16 v[112:115], v[148:151], v[192:195], v[112:115]
	v_mfma_f32_16x16x32_bf16 v[104:107], v[156:159], v[192:195], v[104:107]
	v_mfma_f32_16x16x32_bf16 v[96:99], v[148:151], v[200:203], v[96:99]
	v_mfma_f32_16x16x32_bf16 v[88:91], v[156:159], v[200:203], v[88:91]
	v_mfma_f32_16x16x32_bf16 v[80:83], v[148:151], v[208:211], v[80:83]
	v_mfma_f32_16x16x32_bf16 v[72:75], v[156:159], v[208:211], v[72:75]
	s_setprio 0
	s_setprio 1
	v_mfma_f32_16x16x32_bf16 v[116:119], v[160:163], v[180:183], v[116:119]
	v_mfma_f32_16x16x32_bf16 v[108:111], v[168:171], v[180:183], v[108:111]
	v_mfma_f32_16x16x32_bf16 v[100:103], v[160:163], v[188:191], v[100:103]
	v_mfma_f32_16x16x32_bf16 v[92:95], v[168:171], v[188:191], v[92:95]
	v_mfma_f32_16x16x32_bf16 v[84:87], v[160:163], v[196:199], v[84:87]
	v_mfma_f32_16x16x32_bf16 v[76:79], v[168:171], v[196:199], v[76:79]
	v_mfma_f32_16x16x32_bf16 v[68:71], v[160:163], v[204:207], v[68:71]
	v_mfma_f32_16x16x32_bf16 v[64:67], v[168:171], v[204:207], v[64:67]
	v_mfma_f32_16x16x32_bf16 v[116:119], v[164:167], v[184:187], v[116:119]
	v_mfma_f32_16x16x32_bf16 v[108:111], v[172:175], v[184:187], v[108:111]
	v_mfma_f32_16x16x32_bf16 v[100:103], v[164:167], v[192:195], v[100:103]
	v_mfma_f32_16x16x32_bf16 v[92:95], v[172:175], v[192:195], v[92:95]
	v_mfma_f32_16x16x32_bf16 v[84:87], v[164:167], v[200:203], v[84:87]
	v_mfma_f32_16x16x32_bf16 v[76:79], v[172:175], v[200:203], v[76:79]
	v_mfma_f32_16x16x32_bf16 v[68:71], v[164:167], v[208:211], v[68:71]
	v_mfma_f32_16x16x32_bf16 v[64:67], v[172:175], v[208:211], v[64:67]
	s_setprio 0
	s_barrier
	s_add_i32 s3, s65, s46
	v_lshl_add_u64 v[212:213], s[30:31], 0, v[128:129]
	s_mov_b32 m0, s3
	ds_read_b128 v[180:183], v145 offset:16384
	ds_read_b128 v[184:187], v145 offset:17408
	ds_read_b128 v[188:191], v145 offset:18432
	ds_read_b128 v[192:195], v145 offset:19456
	ds_read_b128 v[196:199], v145 offset:20480
	ds_read_b128 v[200:203], v145 offset:21504
	ds_read_b128 v[204:207], v145 offset:22528
	ds_read_b128 v[208:211], v145 offset:23552
	global_load_lds_dwordx4 v[212:213], off
	s_add_i32 m0, s3, 0x2000
	s_add_u32 s36, s30, 0x40000
	v_lshl_add_u64 v[214:215], s[30:31], 0, v[130:131]
	s_addc_u32 s37, s31, 0
	s_add_i32 s3, s66, s46
	global_load_lds_dwordx4 v[214:215], off
	v_lshl_add_u64 v[216:217], s[36:37], 0, v[128:129]
	s_mov_b32 m0, s3
	v_lshl_add_u64 v[218:219], s[34:35], 0, v[130:131]
	global_load_lds_dwordx4 v[216:217], off
	v_lshl_add_u64 v[216:217], s[36:37], 0, v[130:131]
	s_add_i32 m0, s3, 0x2000
	s_nop 0
	global_load_lds_dwordx4 v[216:217], off
	v_lshl_add_u64 v[216:217], s[34:35], 0, v[128:129]
	s_mov_b32 m0, s47
	s_nop 0
	global_load_lds_dwordx4 v[216:217], off
	s_mov_b32 m0, s60
	s_nop 0
	global_load_lds_dwordx4 v[218:219], off
	s_waitcnt vmcnt(8)
	s_waitcnt lgkmcnt(0)
	s_barrier
; #define PG8_STAGE(bufoff, gbase, voff) do { _Pragma("unroll") for (int _i = 0; _i < 2; ++_i) \
;         __builtin_amdgcn_global_load_lds((const unsigned*)((const char*)(gbase) + (voff)[_i]), (PG8_LAS unsigned*)(lds + (bufoff) + ldsw + _i * 8192), 16, 0, 0); } while (0)
; #define PG8_LDA(dst, b, h) do { _Pragma("unroll") for (int m = 0; m < 4; ++m) _Pragma("unroll") for (int k = 0; k < 2; ++k) dst[m][k] = *(const PG8_LAS bf16x8*)(lds + PG8_SA(b, h) + aoff + m * 2048 + k * 1024); } while (0)
; #define PG8_LDB(dst, b, h) do { _Pragma("unroll") for (int n = 0; n < 2; ++n) _Pragma("unroll") for (int k = 0; k < 2; ++k) dst[n][k] = *(const PG8_LAS bf16x8*)(lds + PG8_SB(b, h) + boff + n * 2048 + k * 1024); } while (0)
; #define PG8_MMA(ai, bj, At, Bt) do { __builtin_amdgcn_s_setprio(1); _Pragma("unroll") for (int m = 0; m < 4; ++m) _Pragma("unroll") for (int n = 0; n < 2; ++n) _Pragma("unroll") for (int k = 0; k < 2; ++k) \
;         acc[ai][bj][m][n] = __builtin_amdgcn_mfma_f32_16x16x32_bf16(Bt[n][k], At[m][k], acc[ai][bj][m][n], 0, 0, 0); __builtin_amdgcn_s_setprio(0); } while (0)
; #define PG8_WAIT_V(n) asm volatile("s_waitcnt vmcnt(" #n ")" ::: "memory")
; template <class Epi, class Sched, bool ALIGN_EPI = false, bool SP2 = false>
; __device__ __forceinline__ void gemm_phase(PG8_LAS unsigned char* lds, const Gemm g, const Sched& S, const Epi& E) {
;     ...
;             PG8_LDB(B0, 0, 0); PG8_LDB(B1, 0, 1); PG8_SCHED; PG8_LDA(At, 0, 0); PG8_STAGE(PG8_SA(1, 1), a1 + hstep, voffA);
;             PG8_WAIT_V(8); PG8_WAIT_L(0); PG8_BAR; PG8_MMA(0, 0, At, B0); PG8_MMA(0, 1, At, B1); PG8_BAR; PG8_SCHED;
;             PG8_LDA(At, 0, 1); PG8_STAGE(PG8_SB(0, 0), b2, voffB); PG8_STAGE(PG8_SB(0, 1), b2 + hstep, voffB); PG8_STAGE(PG8_SA(0, 0), a2, voffA);
;             PG8_WAIT_V(8); PG8_WAIT_L(0); PG8_BAR; PG8_MMA(1, 0, At, B0); PG8_MMA(1, 1, At, B1); PG8_BAR; PG8_SCHED;
;             PG8_LDB(B0, 1, 0); PG8_LDB(B1, 1, 1); PG8_SCHED; PG8_LDA(At, 1, 0); PG8_STAGE(PG8_SA(0, 1), a2 + hstep, voffA);
;             PG8_WAIT_V(8); PG8_WAIT_L(0); PG8_BAR; PG8_MMA(0, 0, At, B0); PG8_MMA(0, 1, At, B1); PG8_BAR; PG8_SCHED;
;             PG8_LDA(At, 1, 1); PG8_STAGE(PG8_SB(1, 0), b3, voffB); PG8_STAGE(PG8_SB(1, 1), b3 + hstep, voffB); PG8_STAGE(PG8_SA(1, 0), a3, voffA);
;             PG8_WAIT_V(8); PG8_WAIT_L(0); PG8_BAR; PG8_MMA(1, 0, At, B0); PG8_MMA(1, 1, At, B1); PG8_BAR; PG8_SCHED;
	s_setprio 1
	s_waitcnt lgkmcnt(0)
	v_mfma_f32_16x16x32_bf16 v[60:63], v[136:139], v[180:183], v[60:63]
	v_mfma_f32_16x16x32_bf16 v[56:59], v[152:155], v[180:183], v[56:59]
	v_mfma_f32_16x16x32_bf16 v[48:51], v[136:139], v[188:191], v[48:51]
	v_mfma_f32_16x16x32_bf16 v[40:43], v[152:155], v[188:191], v[40:43]
	v_mfma_f32_16x16x32_bf16 v[32:35], v[136:139], v[196:199], v[32:35]
	v_mfma_f32_16x16x32_bf16 v[24:27], v[152:155], v[196:199], v[24:27]
	v_mfma_f32_16x16x32_bf16 v[16:19], v[136:139], v[204:207], v[16:19]
	v_mfma_f32_16x16x32_bf16 v[8:11], v[152:155], v[204:207], v[8:11]
	v_mfma_f32_16x16x32_bf16 v[60:63], v[148:151], v[184:187], v[60:63]
	v_mfma_f32_16x16x32_bf16 v[56:59], v[156:159], v[184:187], v[56:59]
	v_mfma_f32_16x16x32_bf16 v[48:51], v[148:151], v[192:195], v[48:51]
	v_mfma_f32_16x16x32_bf16 v[40:43], v[156:159], v[192:195], v[40:43]
	v_mfma_f32_16x16x32_bf16 v[32:35], v[148:151], v[200:203], v[32:35]
	v_mfma_f32_16x16x32_bf16 v[24:27], v[156:159], v[200:203], v[24:27]
	v_mfma_f32_16x16x32_bf16 v[16:19], v[148:151], v[208:211], v[16:19]
	v_mfma_f32_16x16x32_bf16 v[8:11], v[156:159], v[208:211], v[8:11]
	s_setprio 0
	s_setprio 1
	v_mfma_f32_16x16x32_bf16 v[52:55], v[160:163], v[180:183], v[52:55]
	v_mfma_f32_16x16x32_bf16 v[44:47], v[168:171], v[180:183], v[44:47]
	v_mfma_f32_16x16x32_bf16 v[36:39], v[160:163], v[188:191], v[36:39]
	v_mfma_f32_16x16x32_bf16 v[28:31], v[168:171], v[188:191], v[28:31]
	v_mfma_f32_16x16x32_bf16 v[20:23], v[160:163], v[196:199], v[20:23]
	v_mfma_f32_16x16x32_bf16 v[12:15], v[168:171], v[196:199], v[12:15]
	v_mfma_f32_16x16x32_bf16 v[4:7], v[160:163], v[204:207], v[4:7]
	v_mfma_f32_16x16x32_bf16 v[0:3], v[168:171], v[204:207], v[0:3]
	v_mfma_f32_16x16x32_bf16 v[52:55], v[164:167], v[184:187], v[52:55]
	v_mfma_f32_16x16x32_bf16 v[44:47], v[172:175], v[184:187], v[44:47]
	v_mfma_f32_16x16x32_bf16 v[36:39], v[164:167], v[192:195], v[36:39]
	v_mfma_f32_16x16x32_bf16 v[28:31], v[172:175], v[192:195], v[28:31]
	v_mfma_f32_16x16x32_bf16 v[20:23], v[164:167], v[200:203], v[20:23]
	v_mfma_f32_16x16x32_bf16 v[12:15], v[172:175], v[200:203], v[12:15]
	v_mfma_f32_16x16x32_bf16 v[4:7], v[164:167], v[208:211], v[4:7]
	v_mfma_f32_16x16x32_bf16 v[0:3], v[172:175], v[208:211], v[0:3]
	s_setprio 0
	s_barrier
	s_add_i32 s3, 0, 0x18000
	v_add_u32_e32 v147, s3, v141
	s_add_i32 s33, 0, 0x1c000
	ds_read_b128 v[136:139], v147
	ds_read_b128 v[148:151], v147 offset:1024
	ds_read_b128 v[152:155], v147 offset:2048
	ds_read_b128 v[156:159], v147 offset:3072
	v_add_u32_e32 v147, s33, v141
	ds_read_b128 v[160:163], v147
	ds_read_b128 v[164:167], v147 offset:1024
	ds_read_b128 v[168:171], v147 offset:2048
	ds_read_b128 v[172:175], v147 offset:3072
	s_add_u32 s34, s34, 0x40000
	s_addc_u32 s35, s35, 0
	s_mov_b32 m0, s61
	v_lshl_add_u64 v[220:221], s[34:35], 0, v[128:129]
	ds_read_b128 v[180:183], v145 offset:32768
	ds_read_b128 v[184:187], v145 offset:33792
	ds_read_b128 v[188:191], v145 offset:34816
	ds_read_b128 v[192:195], v145 offset:35840
	ds_read_b128 v[196:199], v145 offset:36864
	ds_read_b128 v[200:203], v145 offset:37888
	ds_read_b128 v[204:207], v145 offset:38912
	ds_read_b128 v[208:211], v145 offset:39936
	global_load_lds_dwordx4 v[220:221], off
	v_lshl_add_u64 v[220:221], s[34:35], 0, v[130:131]
	s_mov_b32 m0, s62
	s_nop 0
	global_load_lds_dwordx4 v[220:221], off
	s_waitcnt vmcnt(8)
	s_waitcnt lgkmcnt(0)
	s_barrier
	s_setprio 1
	s_waitcnt lgkmcnt(0)
	v_mfma_f32_16x16x32_bf16 v[124:127], v[136:139], v[180:183], v[124:127]
	v_mfma_f32_16x16x32_bf16 v[120:123], v[152:155], v[180:183], v[120:123]
	v_mfma_f32_16x16x32_bf16 v[112:115], v[136:139], v[188:191], v[112:115]
	v_mfma_f32_16x16x32_bf16 v[104:107], v[152:155], v[188:191], v[104:107]
	v_mfma_f32_16x16x32_bf16 v[96:99], v[136:139], v[196:199], v[96:99]
	v_mfma_f32_16x16x32_bf16 v[88:91], v[152:155], v[196:199], v[88:91]
	v_mfma_f32_16x16x32_bf16 v[80:83], v[136:139], v[204:207], v[80:83]
	v_mfma_f32_16x16x32_bf16 v[72:75], v[152:155], v[204:207], v[72:75]
	v_mfma_f32_16x16x32_bf16 v[124:127], v[148:151], v[184:187], v[124:127]
	v_mfma_f32_16x16x32_bf16 v[120:123], v[156:159], v[184:187], v[120:123]
	v_mfma_f32_16x16x32_bf16 v[112:115], v[148:151], v[192:195], v[112:115]
	v_mfma_f32_16x16x32_bf16 v[104:107], v[156:159], v[192:195], v[104:107]
	v_mfma_f32_16x16x32_bf16 v[96:99], v[148:151], v[200:203], v[96:99]
	v_mfma_f32_16x16x32_bf16 v[88:91], v[156:159], v[200:203], v[88:91]
	v_mfma_f32_16x16x32_bf16 v[80:83], v[148:151], v[208:211], v[80:83]
	v_mfma_f32_16x16x32_bf16 v[72:75], v[156:159], v[208:211], v[72:75]
	s_setprio 0
	s_setprio 1
	v_mfma_f32_16x16x32_bf16 v[116:119], v[160:163], v[180:183], v[116:119]
	v_mfma_f32_16x16x32_bf16 v[108:111], v[168:171], v[180:183], v[108:111]
	v_mfma_f32_16x16x32_bf16 v[100:103], v[160:163], v[188:191], v[100:103]
	v_mfma_f32_16x16x32_bf16 v[92:95], v[168:171], v[188:191], v[92:95]
	v_mfma_f32_16x16x32_bf16 v[84:87], v[160:163], v[196:199], v[84:87]
	v_mfma_f32_16x16x32_bf16 v[76:79], v[168:171], v[196:199], v[76:79]
	v_mfma_f32_16x16x32_bf16 v[68:71], v[160:163], v[204:207], v[68:71]
	v_mfma_f32_16x16x32_bf16 v[64:67], v[168:171], v[204:207], v[64:67]
	v_mfma_f32_16x16x32_bf16 v[116:119], v[164:167], v[184:187], v[116:119]
	v_mfma_f32_16x16x32_bf16 v[108:111], v[172:175], v[184:187], v[108:111]
	v_mfma_f32_16x16x32_bf16 v[100:103], v[164:167], v[192:195], v[100:103]
	v_mfma_f32_16x16x32_bf16 v[92:95], v[172:175], v[192:195], v[92:95]
	v_mfma_f32_16x16x32_bf16 v[84:87], v[164:167], v[200:203], v[84:87]
	v_mfma_f32_16x16x32_bf16 v[76:79], v[172:175], v[200:203], v[76:79]
	v_mfma_f32_16x16x32_bf16 v[68:71], v[164:167], v[208:211], v[68:71]
	v_mfma_f32_16x16x32_bf16 v[64:67], v[172:175], v[208:211], v[64:67]
	s_setprio 0
	s_barrier
; #define PG8_STAGE(bufoff, gbase, voff) do { _Pragma("unroll") for (int _i = 0; _i < 2; ++_i) \
;         __builtin_amdgcn_global_load_lds((const unsigned*)((const char*)(gbase) + (voff)[_i]), (PG8_LAS unsigned*)(lds + (bufoff) + ldsw + _i * 8192), 16, 0, 0); } while (0)
; #define PG8_LDA(dst, b, h) do { _Pragma("unroll") for (int m = 0; m < 4; ++m) _Pragma("unroll") for (int k = 0; k < 2; ++k) dst[m][k] = *(const PG8_LAS bf16x8*)(lds + PG8_SA(b, h) + aoff + m * 2048 + k * 1024); } while (0)
; #define PG8_LDB(dst, b, h) do { _Pragma("unroll") for (int n = 0; n < 2; ++n) _Pragma("unroll") for (int k = 0; k < 2; ++k) dst[n][k] = *(const PG8_LAS bf16x8*)(lds + PG8_SB(b, h) + boff + n * 2048 + k * 1024); } while (0)
; #define PG8_MMA(ai, bj, At, Bt) do { __builtin_amdgcn_s_setprio(1); _Pragma("unroll") for (int m = 0; m < 4; ++m) _Pragma("unroll") for (int n = 0; n < 2; ++n) _Pragma("unroll") for (int k = 0; k < 2; ++k) \
;         acc[ai][bj][m][n] = __builtin_amdgcn_mfma_f32_16x16x32_bf16(Bt[n][k], At[m][k], acc[ai][bj][m][n], 0, 0, 0); __builtin_amdgcn_s_setprio(0); } while (0)
; #define PG8_WAIT_V(n) asm volatile("s_waitcnt vmcnt(" #n ")" ::: "memory")
; #define PG8_WAIT_L(n) asm volatile("s_waitcnt lgkmcnt(" #n ")" ::: "memory")
; #define PG8_BAR __builtin_amdgcn_s_barrier()
; #define PG8_SCHED __builtin_amdgcn_sched_barrier(0)
; template <class Epi, class Sched, bool ALIGN_EPI = false, bool SP2 = false>
; __device__ __forceinline__ void gemm_phase(PG8_LAS unsigned char* lds, const Gemm g, const Sched& S, const Epi& E) {
;     ...
;         for (int t = 0; t < nt; t += 2) {
;             const bool last = (t == nt - 2);
;     ...
;             PG8_LDB(B0, 1, 0); PG8_LDB(B1, 1, 1); PG8_SCHED; PG8_LDA(At, 1, 0); PG8_STAGE(PG8_SA(0, 1), a2 + hstep, voffA);
;             PG8_WAIT_V(8); PG8_WAIT_L(0); PG8_BAR; PG8_MMA(0, 0, At, B0); PG8_MMA(0, 1, At, B1); PG8_BAR; PG8_SCHED;
;             PG8_LDA(At, 1, 1); PG8_STAGE(PG8_SB(1, 0), b3, voffB); PG8_STAGE(PG8_SB(1, 1), b3 + hstep, voffB); PG8_STAGE(PG8_SA(1, 0), a3, voffA);
;             PG8_WAIT_V(8); PG8_WAIT_L(0); PG8_BAR; PG8_MMA(1, 0, At, B0); PG8_MMA(1, 1, At, B1); PG8_BAR; PG8_SCHED;
	s_add_i32 s3, s3, s46
	v_lshl_add_u64 v[212:213], v[212:213], 0, s[14:15]
	s_mov_b32 m0, s3
	ds_read_b128 v[180:183], v145 offset:49152
	ds_read_b128 v[184:187], v145 offset:50176
	ds_read_b128 v[188:191], v145 offset:51200
	ds_read_b128 v[192:195], v145 offset:52224
	ds_read_b128 v[196:199], v145 offset:53248
	ds_read_b128 v[200:203], v145 offset:54272
	ds_read_b128 v[204:207], v145 offset:55296
	ds_read_b128 v[208:211], v145 offset:56320
	global_load_lds_dwordx4 v[212:213], off
	s_add_i32 m0, s3, 0x2000
	s_add_u32 s30, s30, 0x40080
	v_lshl_add_u64 v[212:213], v[214:215], 0, s[14:15]
	s_addc_u32 s31, s31, 0
	s_add_i32 s3, s33, s46
	global_load_lds_dwordx4 v[212:213], off
	v_lshl_add_u64 v[212:213], s[30:31], 0, v[128:129]
	s_mov_b32 m0, s3
	s_nop 0
	global_load_lds_dwordx4 v[212:213], off
	v_lshl_add_u64 v[212:213], s[30:31], 0, v[130:131]
	s_add_i32 m0, s3, 0x2000
	s_nop 0
	global_load_lds_dwordx4 v[212:213], off
	v_lshl_add_u64 v[212:213], v[216:217], 0, s[14:15]
	s_mov_b32 m0, s63
	s_nop 0
	global_load_lds_dwordx4 v[212:213], off
	v_lshl_add_u64 v[212:213], v[218:219], 0, s[14:15]
	s_mov_b32 m0, s64
	s_nop 0
	global_load_lds_dwordx4 v[212:213], off
	s_waitcnt vmcnt(8)
	s_waitcnt lgkmcnt(0)
	s_barrier
	s_setprio 1
	s_waitcnt lgkmcnt(0)
	v_mfma_f32_16x16x32_bf16 v[60:63], v[136:139], v[180:183], v[60:63]
	v_mfma_f32_16x16x32_bf16 v[56:59], v[152:155], v[180:183], v[56:59]
	v_mfma_f32_16x16x32_bf16 v[48:51], v[136:139], v[188:191], v[48:51]
	v_mfma_f32_16x16x32_bf16 v[40:43], v[152:155], v[188:191], v[40:43]
	v_mfma_f32_16x16x32_bf16 v[32:35], v[136:139], v[196:199], v[32:35]
	v_mfma_f32_16x16x32_bf16 v[24:27], v[152:155], v[196:199], v[24:27]
	v_mfma_f32_16x16x32_bf16 v[16:19], v[136:139], v[204:207], v[16:19]
	v_mfma_f32_16x16x32_bf16 v[8:11], v[152:155], v[204:207], v[8:11]
	v_mfma_f32_16x16x32_bf16 v[60:63], v[148:151], v[184:187], v[60:63]
	v_mfma_f32_16x16x32_bf16 v[56:59], v[156:159], v[184:187], v[56:59]
	v_mfma_f32_16x16x32_bf16 v[48:51], v[148:151], v[192:195], v[48:51]
	v_mfma_f32_16x16x32_bf16 v[40:43], v[156:159], v[192:195], v[40:43]
	v_mfma_f32_16x16x32_bf16 v[32:35], v[148:151], v[200:203], v[32:35]
	v_mfma_f32_16x16x32_bf16 v[24:27], v[156:159], v[200:203], v[24:27]
	v_mfma_f32_16x16x32_bf16 v[16:19], v[148:151], v[208:211], v[16:19]
	v_mfma_f32_16x16x32_bf16 v[8:11], v[156:159], v[208:211], v[8:11]
	s_setprio 0
	s_setprio 1
	v_mfma_f32_16x16x32_bf16 v[52:55], v[160:163], v[180:183], v[52:55]
	v_mfma_f32_16x16x32_bf16 v[44:47], v[168:171], v[180:183], v[44:47]
	v_mfma_f32_16x16x32_bf16 v[36:39], v[160:163], v[188:191], v[36:39]
	v_mfma_f32_16x16x32_bf16 v[28:31], v[168:171], v[188:191], v[28:31]
	v_mfma_f32_16x16x32_bf16 v[20:23], v[160:163], v[196:199], v[20:23]
	v_mfma_f32_16x16x32_bf16 v[12:15], v[168:171], v[196:199], v[12:15]
	v_mfma_f32_16x16x32_bf16 v[4:7], v[160:163], v[204:207], v[4:7]
	v_mfma_f32_16x16x32_bf16 v[0:3], v[168:171], v[204:207], v[0:3]
	v_mfma_f32_16x16x32_bf16 v[52:55], v[164:167], v[184:187], v[52:55]
	v_mfma_f32_16x16x32_bf16 v[44:47], v[172:175], v[184:187], v[44:47]
	v_mfma_f32_16x16x32_bf16 v[36:39], v[164:167], v[192:195], v[36:39]
	v_mfma_f32_16x16x32_bf16 v[28:31], v[172:175], v[192:195], v[28:31]
	v_mfma_f32_16x16x32_bf16 v[20:23], v[164:167], v[200:203], v[20:23]
	v_mfma_f32_16x16x32_bf16 v[12:15], v[172:175], v[200:203], v[12:15]
	v_mfma_f32_16x16x32_bf16 v[4:7], v[164:167], v[208:211], v[4:7]
	v_mfma_f32_16x16x32_bf16 v[0:3], v[172:175], v[208:211], v[0:3]
	s_setprio 0
	s_barrier
	s_add_i32 s71, s71, 2
	s_add_u32 s28, s28, 0x100
	s_addc_u32 s29, s29, 0
	s_add_u32 s69, s69, 0x100
	s_addc_u32 s70, s70, 0
	s_cmp_gt_u32 s71, 5
	s_cbranch_scc0 .LBB0_1059
; #define PG8_BAR __builtin_amdgcn_s_barrier()
; template <class Epi, class Sched, bool ALIGN_EPI = false, bool SP2 = false>
; __device__ __forceinline__ void gemm_phase(PG8_LAS unsigned char* lds, const Gemm g, const Sched& S, const Epi& E) {
;     ...
;         }
;         if constexpr (ALIGN_EPI) { if (wr == 0) PG8_BAR; }
;         if constexpr (!Epi::AFTER_DRAIN) { E(acc, cur, wr, wc, fr, fq); S.done(cur); }
;         if (!has_next) break;
	s_and_b32 s100, s2, 15
	v_readfirstlane_b32 s101, v178
	s_lshl_b32 s98, s100, 18
	s_lshr_b32 s101, s101, 6
	s_lshl_b32 s99, s101, 15
	s_add_u32 s98, s98, s99
	s_lshl_b32 s100, s100, 3
	s_add_u32 s100, s100, s101
	s_lshl_b32 s100, s100, 2
	s_add_u32 s98, s54, s98
	s_addc_u32 s99, s55, 0
	s_add_u32 s98, s98, 0x2300000
	s_addc_u32 s99, s99, 0
	s_add_u32 s100, s54, s100
	s_addc_u32 s101, s55, 0
	s_add_u32 s100, s100, 0x22a2000
	s_addc_u32 s101, s101, 0
	v_lshlrev_b32_e32 v160, 4, v176
	v_mov_b32_e32 v161, 0
	s_cmp_lt_u32 s2, 16
	s_cbranch_scc1 .Lsk_reader_p8
	global_store_dwordx4 v160, v[0:3], s[98:99]
	s_add_u32 s98, s98, 0x400
	s_addc_u32 s99, s99, 0
	global_store_dwordx4 v160, v[4:7], s[98:99]
	s_add_u32 s98, s98, 0x400
	s_addc_u32 s99, s99, 0
	global_store_dwordx4 v160, v[8:11], s[98:99]
	s_add_u32 s98, s98, 0x400
	s_addc_u32 s99, s99, 0
	global_store_dwordx4 v160, v[12:15], s[98:99]
	s_add_u32 s98, s98, 0x400
	s_addc_u32 s99, s99, 0
	global_store_dwordx4 v160, v[16:19], s[98:99]
	s_add_u32 s98, s98, 0x400
	s_addc_u32 s99, s99, 0
	global_store_dwordx4 v160, v[20:23], s[98:99]
	s_add_u32 s98, s98, 0x400
	s_addc_u32 s99, s99, 0
	global_store_dwordx4 v160, v[24:27], s[98:99]
	s_add_u32 s98, s98, 0x400
	s_addc_u32 s99, s99, 0
	global_store_dwordx4 v160, v[28:31], s[98:99]
	s_add_u32 s98, s98, 0x400
	s_addc_u32 s99, s99, 0
	global_store_dwordx4 v160, v[32:35], s[98:99]
	s_add_u32 s98, s98, 0x400
	s_addc_u32 s99, s99, 0
	global_store_dwordx4 v160, v[36:39], s[98:99]
	s_add_u32 s98, s98, 0x400
	s_addc_u32 s99, s99, 0
	global_store_dwordx4 v160, v[40:43], s[98:99]
	s_add_u32 s98, s98, 0x400
	s_addc_u32 s99, s99, 0
	global_store_dwordx4 v160, v[44:47], s[98:99]
	s_add_u32 s98, s98, 0x400
	s_addc_u32 s99, s99, 0
	global_store_dwordx4 v160, v[48:51], s[98:99]
	s_add_u32 s98, s98, 0x400
	s_addc_u32 s99, s99, 0
	global_store_dwordx4 v160, v[52:55], s[98:99]
	s_add_u32 s98, s98, 0x400
	s_addc_u32 s99, s99, 0
	global_store_dwordx4 v160, v[56:59], s[98:99]
	s_add_u32 s98, s98, 0x400
	s_addc_u32 s99, s99, 0
	global_store_dwordx4 v160, v[60:63], s[98:99]
	s_add_u32 s98, s98, 0x400
	s_addc_u32 s99, s99, 0
	global_store_dwordx4 v160, v[64:67], s[98:99]
	s_add_u32 s98, s98, 0x400
	s_addc_u32 s99, s99, 0
	global_store_dwordx4 v160, v[68:71], s[98:99]
	s_add_u32 s98, s98, 0x400
	s_addc_u32 s99, s99, 0
	global_store_dwordx4 v160, v[72:75], s[98:99]
	s_add_u32 s98, s98, 0x400
	s_addc_u32 s99, s99, 0
	global_store_dwordx4 v160, v[76:79], s[98:99]
	s_add_u32 s98, s98, 0x400
	s_addc_u32 s99, s99, 0
	global_store_dwordx4 v160, v[80:83], s[98:99]
	s_add_u32 s98, s98, 0x400
	s_addc_u32 s99, s99, 0
	global_store_dwordx4 v160, v[84:87], s[98:99]
	s_add_u32 s98, s98, 0x400
	s_addc_u32 s99, s99, 0
	global_store_dwordx4 v160, v[88:91], s[98:99]
	s_add_u32 s98, s98, 0x400
	s_addc_u32 s99, s99, 0
	global_store_dwordx4 v160, v[92:95], s[98:99]
	s_add_u32 s98, s98, 0x400
	s_addc_u32 s99, s99, 0
	global_store_dwordx4 v160, v[96:99], s[98:99]
	s_add_u32 s98, s98, 0x400
	s_addc_u32 s99, s99, 0
	global_store_dwordx4 v160, v[100:103], s[98:99]
	s_add_u32 s98, s98, 0x400
	s_addc_u32 s99, s99, 0
	global_store_dwordx4 v160, v[104:107], s[98:99]
	s_add_u32 s98, s98, 0x400
	s_addc_u32 s99, s99, 0
	global_store_dwordx4 v160, v[108:111], s[98:99]
	s_add_u32 s98, s98, 0x400
	s_addc_u32 s99, s99, 0
	global_store_dwordx4 v160, v[112:115], s[98:99]
	s_add_u32 s98, s98, 0x400
	s_addc_u32 s99, s99, 0
	global_store_dwordx4 v160, v[116:119], s[98:99]
	s_add_u32 s98, s98, 0x400
	s_addc_u32 s99, s99, 0
	global_store_dwordx4 v160, v[120:123], s[98:99]
	s_add_u32 s98, s98, 0x400
	s_addc_u32 s99, s99, 0
	global_store_dwordx4 v160, v[124:127], s[98:99]
	s_add_u32 s98, s98, 0x400
	s_addc_u32 s99, s99, 0
	s_waitcnt vmcnt(0)
	buffer_wbl2 sc1
	s_waitcnt vmcnt(0)
	s_mov_b64 exec, 1
	v_mov_b32_e32 v162, 1
	global_atomic_add v161, v162, s[100:101]
	s_mov_b64 exec, -1
	s_branch .LBB0_1051

; #define PG8_BAR __builtin_amdgcn_s_barrier()
; template <class Epi, class Sched, bool ALIGN_EPI = false, bool SP2 = false>
; __device__ __forceinline__ void gemm_phase(PG8_LAS unsigned char* lds, const Gemm g, const Sched& S, const Epi& E) {
;     ...
;         }
;         if constexpr (ALIGN_EPI) { if (wr == 0) PG8_BAR; }
;         if constexpr (!Epi::AFTER_DRAIN) { E(acc, cur, wr, wc, fr, fq); S.done(cur); }
;         if (!has_next) break;
.Lsk_loop_p8:
	global_load_dword v163, v161, s[100:101] sc1
	s_waitcnt vmcnt(0)
	v_cmp_lt_u32_e32 vcc, 0, v163
	s_cbranch_vccnz .Lsk_go_p8
	v_add_u32_e32 v162, 1, v162
	v_cmp_gt_u32_e32 vcc, 0x100000, v162
	s_sleep 1
	s_cbranch_vccnz .Lsk_loop_p8
.Lsk_go_p8:
	buffer_inv sc1
	s_waitcnt vmcnt(0)
	global_load_dwordx4 v[180:183], v160, s[98:99]
	s_add_u32 s98, s98, 0x400
	s_addc_u32 s99, s99, 0
	global_load_dwordx4 v[184:187], v160, s[98:99]
	s_add_u32 s98, s98, 0x400
	s_addc_u32 s99, s99, 0
	global_load_dwordx4 v[188:191], v160, s[98:99]
	s_add_u32 s98, s98, 0x400
	s_addc_u32 s99, s99, 0
	global_load_dwordx4 v[192:195], v160, s[98:99]
	s_add_u32 s98, s98, 0x400
	s_addc_u32 s99, s99, 0
	global_load_dwordx4 v[196:199], v160, s[98:99]
	s_add_u32 s98, s98, 0x400
	s_addc_u32 s99, s99, 0
	global_load_dwordx4 v[200:203], v160, s[98:99]
	s_add_u32 s98, s98, 0x400
	s_addc_u32 s99, s99, 0
	global_load_dwordx4 v[204:207], v160, s[98:99]
	s_add_u32 s98, s98, 0x400
	s_addc_u32 s99, s99, 0
	global_load_dwordx4 v[208:211], v160, s[98:99]
	s_add_u32 s98, s98, 0x400
	s_addc_u32 s99, s99, 0
	global_load_dwordx4 v[212:215], v160, s[98:99]
	s_add_u32 s98, s98, 0x400
	s_addc_u32 s99, s99, 0
	global_load_dwordx4 v[216:219], v160, s[98:99]
	s_add_u32 s98, s98, 0x400
	s_addc_u32 s99, s99, 0
	global_load_dwordx4 v[220:223], v160, s[98:99]
	s_add_u32 s98, s98, 0x400
	s_addc_u32 s99, s99, 0
	global_load_dwordx4 v[224:227], v160, s[98:99]
	s_add_u32 s98, s98, 0x400
	s_addc_u32 s99, s99, 0
	global_load_dwordx4 v[228:231], v160, s[98:99]
	s_add_u32 s98, s98, 0x400
	s_addc_u32 s99, s99, 0
	global_load_dwordx4 v[232:235], v160, s[98:99]
	s_add_u32 s98, s98, 0x400
	s_addc_u32 s99, s99, 0
	global_load_dwordx4 v[236:239], v160, s[98:99]
	s_add_u32 s98, s98, 0x400
	s_addc_u32 s99, s99, 0
	global_load_dwordx4 v[240:243], v160, s[98:99]
	s_add_u32 s98, s98, 0x400
	s_addc_u32 s99, s99, 0
	s_waitcnt vmcnt(8)
	v_add_f32_e32 v0, v0, v180
	v_add_f32_e32 v1, v1, v181
	v_add_f32_e32 v2, v2, v182
	v_add_f32_e32 v3, v3, v183
	v_add_f32_e32 v4, v4, v184
	v_add_f32_e32 v5, v5, v185
	v_add_f32_e32 v6, v6, v186
	v_add_f32_e32 v7, v7, v187
	v_add_f32_e32 v8, v8, v188
	v_add_f32_e32 v9, v9, v189
	v_add_f32_e32 v10, v10, v190
	v_add_f32_e32 v11, v11, v191
	v_add_f32_e32 v12, v12, v192
	v_add_f32_e32 v13, v13, v193
	v_add_f32_e32 v14, v14, v194
	v_add_f32_e32 v15, v15, v195
	v_add_f32_e32 v16, v16, v196
	v_add_f32_e32 v17, v17, v197
	v_add_f32_e32 v18, v18, v198
	v_add_f32_e32 v19, v19, v199
	v_add_f32_e32 v20, v20, v200
	v_add_f32_e32 v21, v21, v201
	v_add_f32_e32 v22, v22, v202
	v_add_f32_e32 v23, v23, v203
	v_add_f32_e32 v24, v24, v204
	v_add_f32_e32 v25, v25, v205
	v_add_f32_e32 v26, v26, v206
	v_add_f32_e32 v27, v27, v207
	v_add_f32_e32 v28, v28, v208
	v_add_f32_e32 v29, v29, v209
	v_add_f32_e32 v30, v30, v210
	v_add_f32_e32 v31, v31, v211
	global_load_dwordx4 v[180:183], v160, s[98:99]
	s_add_u32 s98, s98, 0x400
	s_addc_u32 s99, s99, 0
	global_load_dwordx4 v[184:187], v160, s[98:99]
	s_add_u32 s98, s98, 0x400
	s_addc_u32 s99, s99, 0
	global_load_dwordx4 v[188:191], v160, s[98:99]
	s_add_u32 s98, s98, 0x400
	s_addc_u32 s99, s99, 0
	global_load_dwordx4 v[192:195], v160, s[98:99]
	s_add_u32 s98, s98, 0x400
	s_addc_u32 s99, s99, 0
	global_load_dwordx4 v[196:199], v160, s[98:99]
	s_add_u32 s98, s98, 0x400
	s_addc_u32 s99, s99, 0
	global_load_dwordx4 v[200:203], v160, s[98:99]
	s_add_u32 s98, s98, 0x400
	s_addc_u32 s99, s99, 0
	global_load_dwordx4 v[204:207], v160, s[98:99]
	s_add_u32 s98, s98, 0x400
	s_addc_u32 s99, s99, 0
	global_load_dwordx4 v[208:211], v160, s[98:99]
	s_add_u32 s98, s98, 0x400
	s_addc_u32 s99, s99, 0
	s_waitcnt vmcnt(8)
	v_add_f32_e32 v32, v32, v212
	v_add_f32_e32 v33, v33, v213
	v_add_f32_e32 v34, v34, v214
	v_add_f32_e32 v35, v35, v215
	v_add_f32_e32 v36, v36, v216
	v_add_f32_e32 v37, v37, v217
	v_add_f32_e32 v38, v38, v218
	v_add_f32_e32 v39, v39, v219
	v_add_f32_e32 v40, v40, v220
	v_add_f32_e32 v41, v41, v221
	v_add_f32_e32 v42, v42, v222
	v_add_f32_e32 v43, v43, v223
	v_add_f32_e32 v44, v44, v224
	v_add_f32_e32 v45, v45, v225
	v_add_f32_e32 v46, v46, v226
	v_add_f32_e32 v47, v47, v227
	v_add_f32_e32 v48, v48, v228
	v_add_f32_e32 v49, v49, v229
	v_add_f32_e32 v50, v50, v230
	v_add_f32_e32 v51, v51, v231
	v_add_f32_e32 v52, v52, v232
	v_add_f32_e32 v53, v53, v233
	v_add_f32_e32 v54, v54, v234
	v_add_f32_e32 v55, v55, v235
	v_add_f32_e32 v56, v56, v236
	v_add_f32_e32 v57, v57, v237
	v_add_f32_e32 v58, v58, v238
	v_add_f32_e32 v59, v59, v239
	v_add_f32_e32 v60, v60, v240
	v_add_f32_e32 v61, v61, v241
	v_add_f32_e32 v62, v62, v242
	v_add_f32_e32 v63, v63, v243
	global_load_dwordx4 v[212:215], v160, s[98:99]
	s_add_u32 s98, s98, 0x400
	s_addc_u32 s99, s99, 0
	global_load_dwordx4 v[216:219], v160, s[98:99]
	s_add_u32 s98, s98, 0x400
	s_addc_u32 s99, s99, 0
	global_load_dwordx4 v[220:223], v160, s[98:99]
	s_add_u32 s98, s98, 0x400
	s_addc_u32 s99, s99, 0
	global_load_dwordx4 v[224:227], v160, s[98:99]
	s_add_u32 s98, s98, 0x400
	s_addc_u32 s99, s99, 0
	global_load_dwordx4 v[228:231], v160, s[98:99]
	s_add_u32 s98, s98, 0x400
	s_addc_u32 s99, s99, 0
	global_load_dwordx4 v[232:235], v160, s[98:99]
	s_add_u32 s98, s98, 0x400
	s_addc_u32 s99, s99, 0
	global_load_dwordx4 v[236:239], v160, s[98:99]
	s_add_u32 s98, s98, 0x400
	s_addc_u32 s99, s99, 0
	global_load_dwordx4 v[240:243], v160, s[98:99]
	s_add_u32 s98, s98, 0x400
	s_addc_u32 s99, s99, 0
	s_waitcnt vmcnt(8)
; __device__ __forceinline__ u32x2 pk4(f32x4 v) { u32x2 w; w.x = cvt_pk_bf16(v[0], v[1]); w.y = cvt_pk_bf16(v[2], v[3]); return w; }
; __device__ __forceinline__ f32x4 up4(u32x2 w) { return (f32x4){bf_lo(w.x), bf_hi(w.x), bf_lo(w.y), bf_hi(w.y)}; }
;     __device__ __forceinline__ void operator()(const AccT& acc, const pg8::Unit& u, int wr, int wc, int fr, int fq) const {
;         const int col0 = u.pn * 256 + wc * 32 + 4 * fq, row0 = row_base + u.pm * 256 + wr * 64 + fr;
; #pragma unroll
;         for (int ai = 0; ai < 2; ++ai)
; #pragma unroll
;             for (int m = 0; m < 4; ++m) { const int row = row0 + ai * 128 + m * 16; float ss = 0.f;
; #pragma unroll
;                 for (int bj = 0; bj < 2; ++bj)
; #pragma unroll
;                     for (int n = 0; n < 2; ++n) { f32x4 v = acc[ai][bj][m][n]; const size_t idx = (size_t)row * 1024 + col0 + bj * 128 + n * 16;
;                         if (MODE == 0) v = v * up4(*(const u32x2*)(io + idx));
;                         else if (MODE == 1) v = up4(*(const u32x2*)(io + idx)) + up4(*(const u32x2*)(g2 + idx)) * v;
;                         else ss += (v[0] * v[0] + v[1] * v[1]) + (v[2] * v[2] + v[3] * v[3]);
;                         if (!DRYE || v[0] == 123.456f) *(u32x2*)(io + idx) = pk4(v); }
;                 if (MODE == 2 && !DRYE) { ss += __shfl_xor(ss, 16); ss += __shfl_xor(ss, 32); if (fq == 0) atomicAdd(rowss + row, ss); } }
	v_add_f32_e32 v64, v64, v180
	v_add_f32_e32 v65, v65, v181
	v_add_f32_e32 v66, v66, v182
	v_add_f32_e32 v67, v67, v183
	v_add_f32_e32 v68, v68, v184
	v_add_f32_e32 v69, v69, v185
	v_add_f32_e32 v70, v70, v186
	v_add_f32_e32 v71, v71, v187
	v_add_f32_e32 v72, v72, v188
	v_add_f32_e32 v73, v73, v189
	v_add_f32_e32 v74, v74, v190
	v_add_f32_e32 v75, v75, v191
	v_add_f32_e32 v76, v76, v192
	v_add_f32_e32 v77, v77, v193
	v_add_f32_e32 v78, v78, v194
	v_add_f32_e32 v79, v79, v195
	v_add_f32_e32 v80, v80, v196
	v_add_f32_e32 v81, v81, v197
	v_add_f32_e32 v82, v82, v198
	v_add_f32_e32 v83, v83, v199
	v_add_f32_e32 v84, v84, v200
	v_add_f32_e32 v85, v85, v201
	v_add_f32_e32 v86, v86, v202
	v_add_f32_e32 v87, v87, v203
	v_add_f32_e32 v88, v88, v204
	v_add_f32_e32 v89, v89, v205
	v_add_f32_e32 v90, v90, v206
	v_add_f32_e32 v91, v91, v207
	v_add_f32_e32 v92, v92, v208
	v_add_f32_e32 v93, v93, v209
	v_add_f32_e32 v94, v94, v210
	v_add_f32_e32 v95, v95, v211
	s_waitcnt vmcnt(0)
	v_add_f32_e32 v96, v96, v212
	v_add_f32_e32 v97, v97, v213
	v_add_f32_e32 v98, v98, v214
	v_add_f32_e32 v99, v99, v215
	v_add_f32_e32 v100, v100, v216
	v_add_f32_e32 v101, v101, v217
	v_add_f32_e32 v102, v102, v218
	v_add_f32_e32 v103, v103, v219
	v_add_f32_e32 v104, v104, v220
	v_add_f32_e32 v105, v105, v221
	v_add_f32_e32 v106, v106, v222
	v_add_f32_e32 v107, v107, v223
	v_add_f32_e32 v108, v108, v224
	v_add_f32_e32 v109, v109, v225
	v_add_f32_e32 v110, v110, v226
	v_add_f32_e32 v111, v111, v227
	v_add_f32_e32 v112, v112, v228
	v_add_f32_e32 v113, v113, v229
	v_add_f32_e32 v114, v114, v230
	v_add_f32_e32 v115, v115, v231
	v_add_f32_e32 v116, v116, v232
	v_add_f32_e32 v117, v117, v233
	v_add_f32_e32 v118, v118, v234
	v_add_f32_e32 v119, v119, v235
	v_add_f32_e32 v120, v120, v236
	v_add_f32_e32 v121, v121, v237
	v_add_f32_e32 v122, v122, v238
	v_add_f32_e32 v123, v123, v239
	v_add_f32_e32 v124, v124, v240
	v_add_f32_e32 v125, v125, v241
	v_add_f32_e32 v126, v126, v242
	v_add_f32_e32 v127, v127, v243
	v_and_b32_e32 v147, 64, v146
	v_xor_b32_e32 v139, 16, v146
	v_add_u32_e32 v147, 64, v147
	v_cmp_lt_i32_e32 vcc, v139, v147
	v_lshl_add_u32 v149, s26, 8, v140
	v_add_u32_e32 v138, 0x4000, v149
	v_cndmask_b32_e32 v139, v146, v139, vcc
	v_lshlrev_b32_e32 v148, 2, v139
	v_xor_b32_e32 v139, 32, v146
	v_cmp_lt_i32_e32 vcc, v139, v147
	v_lshl_or_b32 v136, s27, 8, v142
	v_mul_f32_e32 v152, v125, v125
	v_cndmask_b32_e32 v139, v146, v139, vcc
	v_lshlrev_b32_e32 v147, 2, v139
	v_ashrrev_i32_e32 v139, 31, v138
	v_lshlrev_b64 v[150:151], 11, v[138:139]
	v_mul_f32_e32 v153, v127, v127
	v_ashrrev_i32_e32 v137, 31, v136
	v_fmac_f32_e32 v152, v124, v124
	v_fmac_f32_e32 v153, v126, v126
	v_cvt_pk_bf16_f32 v124, v124, v125
	v_cvt_pk_bf16_f32 v125, v126, v127
	v_lshl_add_u64 v[126:127], s[8:9], 0, v[150:151]
	v_lshl_add_u64 v[126:127], v[136:137], 1, v[126:127]
	global_store_dwordx2 v[126:127], v[124:125], off
	v_mul_f32_e32 v124, v121, v121
	v_mul_f32_e32 v125, v123, v123
	v_fmac_f32_e32 v124, v120, v120
	v_fmac_f32_e32 v125, v122, v122
	v_add_f32_e32 v124, v124, v125
	v_cvt_pk_bf16_f32 v120, v120, v121
	v_mul_f32_e32 v121, v117, v117
	v_mul_f32_e32 v125, v119, v119
	v_add_f32_e32 v152, v152, v153
	v_fmac_f32_e32 v121, v116, v116
	v_fmac_f32_e32 v125, v118, v118
	v_add_f32_e32 v124, v152, v124
	v_add_f32_e32 v121, v121, v125
	v_add_f32_e32 v121, v124, v121
	v_mul_f32_e32 v124, v109, v109
	v_mul_f32_e32 v125, v111, v111
	v_fmac_f32_e32 v124, v108, v108
	v_fmac_f32_e32 v125, v110, v110
	v_add_f32_e32 v124, v124, v125
	v_add_f32_e32 v124, v121, v124
	ds_bpermute_b32 v125, v148, v124
	v_cvt_pk_bf16_f32 v121, v122, v123
	global_store_dwordx2 v[126:127], v[120:121], off offset:32
	v_cvt_pk_bf16_f32 v120, v116, v117
	v_cvt_pk_bf16_f32 v121, v118, v119
	s_waitcnt lgkmcnt(0)
	v_add_f32_e32 v116, v124, v125
	ds_bpermute_b32 v117, v147, v116
	v_cvt_pk_bf16_f32 v108, v108, v109
	v_cvt_pk_bf16_f32 v109, v110, v111
	global_store_dwordx2 v[126:127], v[120:121], off offset:256
	global_store_dwordx2 v[126:127], v[108:109], off offset:288
	s_and_saveexec_b64 s[26:27], s[0:1]
	s_cbranch_execz .LBB0_1062
	v_lshl_add_u64 v[108:109], v[138:139], 2, s[10:11]
	s_waitcnt lgkmcnt(0)
	v_add_f32_e32 v110, v116, v117
	global_atomic_add_f32 v[108:109], v110, off

; #define PG8_BAR __builtin_amdgcn_s_barrier()
; template <class Epi, class Sched, bool ALIGN_EPI = false, bool SP2 = false>
; __device__ __forceinline__ void gemm_phase(PG8_LAS unsigned char* lds, const Gemm g, const Sched& S, const Epi& E) {
;     ...
;         }
;         if constexpr (ALIGN_EPI) { if (wr == 0) PG8_BAR; }
;         if constexpr (!Epi::AFTER_DRAIN) { E(acc, cur, wr, wc, fr, fq); S.done(cur); }
;         if (!has_next) break;
.Lsk_loop_p12:
	global_load_dword v163, v161, s[100:101] sc1
	s_waitcnt vmcnt(0)
	v_cmp_lt_u32_e32 vcc, 1, v163
	s_cbranch_vccnz .Lsk_go_p12
	v_add_u32_e32 v162, 1, v162
	v_cmp_gt_u32_e32 vcc, 0x100000, v162
	s_sleep 1
	s_cbranch_vccnz .Lsk_loop_p12
